# gate/up GEMM: first K iteration peeled with zero C operand, accumulator zeroing pass (32 LDS reads per unit per wave) removed
# speedup vs baseline: 1.0140x; 1.0040x over previous
.LBB0_957:
	s_lshl_b32 s21, s8, 10
	s_add_i32 s21, s21, 0
	s_add_i32 s21, s21, 0x20000
	v_lshl_add_u32 v143, v147, 2, s21
	v_lshl_add_u32 v145, v148, 2, s21
	s_add_u32 s21, s30, 0x100
	s_addc_u32 s27, s31, 0
	s_add_u32 s30, s12, 0x80
	s_addc_u32 s31, s13, 0
	s_mov_b32 s29, -2
	s_add_u32 s42, s30, 0x80
	v_add_u32_e32 v64, s9, v133
	s_addc_u32 s43, s31, 0
	ds_read_b128 v[152:155], v64
	ds_read_b128 v[156:159], v64 offset:1024
	ds_read_b128 v[166:169], v64 offset:2048
	ds_read_b128 v[170:173], v64 offset:3072
	v_add_u32_e32 v64, s11, v133
	s_cmp_eq_u32 s29, 4
	ds_read_b128 v[174:177], v64
	ds_read_b128 v[178:181], v64 offset:1024
	ds_read_b128 v[182:185], v64 offset:2048
	ds_read_b128 v[186:189], v64 offset:3072
	s_cselect_b64 s[40:41], -1, 0
	s_and_b64 s[38:39], s[40:41], exec
	s_cselect_b32 s44, s22, s21
	s_cselect_b32 s43, s13, s43
	s_cselect_b32 s42, s12, s42
	s_cselect_b32 s45, s23, s27
	s_add_u32 s38, s44, 0x80
	s_addc_u32 s39, s45, 0
	s_and_b64 vcc, s[4:5], s[40:41]
	s_add_u32 s40, s42, 0x80
	s_addc_u32 s41, s43, 0
	s_add_i32 m0, s52, 0xc000
	ds_read_b128 v[190:193], v131
	ds_read_b128 v[194:197], v131 offset:1024
	ds_read_b128 v[198:201], v131 offset:2048
	ds_read_b128 v[202:205], v131 offset:3072
	ds_read_b128 v[206:209], v131 offset:4096
	ds_read_b128 v[210:213], v131 offset:5120
	ds_read_b128 v[214:217], v131 offset:6144
	ds_read_b128 v[218:221], v131 offset:7168
	global_load_lds_dwordx4 v141, s[30:31]
	s_add_i32 m0, s52, 0xe000
	s_nop 0
	global_load_lds_dwordx4 v151, s[30:31]
	s_waitcnt vmcnt(8)
	s_waitcnt lgkmcnt(0)
	s_barrier
	s_setprio 1
	s_waitcnt lgkmcnt(0)
	v_mfma_scale_f32_16x16x128_f8f6f4 v[120:123], v[152:159], v[190:197], 0, v149, v149 op_sel_hi:[0,0,0]
	v_mfma_scale_f32_16x16x128_f8f6f4 v[112:115], v[166:173], v[190:197], 0, v149, v149 op_sel_hi:[0,0,0]
	v_mfma_scale_f32_16x16x128_f8f6f4 v[104:107], v[152:159], v[198:205], 0, v149, v149 op_sel_hi:[0,0,0]
	v_mfma_scale_f32_16x16x128_f8f6f4 v[96:99], v[166:173], v[198:205], 0, v149, v149 op_sel_hi:[0,0,0]
	v_mfma_scale_f32_16x16x128_f8f6f4 v[230:233], v[166:173], v[214:221], 0, v149, v149 op_sel_hi:[0,0,0]
	v_mfma_scale_f32_16x16x128_f8f6f4 v[160:163], v[152:159], v[206:213], 0, v149, v149 op_sel_hi:[0,0,0]
	v_mfma_scale_f32_16x16x128_f8f6f4 v[222:225], v[166:173], v[206:213], 0, v149, v149 op_sel_hi:[0,0,0]
	v_mfma_scale_f32_16x16x128_f8f6f4 v[226:229], v[152:159], v[214:221], 0, v149, v149 op_sel_hi:[0,0,0]
	s_setprio 0
	s_setprio 1
	v_mfma_scale_f32_16x16x128_f8f6f4 v[124:127], v[174:181], v[190:197], 0, v149, v149 op_sel_hi:[0,0,0]
	v_mfma_scale_f32_16x16x128_f8f6f4 v[116:119], v[182:189], v[190:197], 0, v149, v149 op_sel_hi:[0,0,0]
	v_mfma_scale_f32_16x16x128_f8f6f4 v[108:111], v[174:181], v[198:205], 0, v149, v149 op_sel_hi:[0,0,0]
	v_mfma_scale_f32_16x16x128_f8f6f4 v[100:103], v[182:189], v[198:205], 0, v149, v149 op_sel_hi:[0,0,0]
	v_mfma_scale_f32_16x16x128_f8f6f4 v[190:193], v[174:181], v[206:213], 0, v149, v149 op_sel_hi:[0,0,0]
	v_mfma_scale_f32_16x16x128_f8f6f4 v[194:197], v[182:189], v[206:213], 0, v149, v149 op_sel_hi:[0,0,0]
	v_mfma_scale_f32_16x16x128_f8f6f4 v[198:201], v[174:181], v[214:221], 0, v149, v149 op_sel_hi:[0,0,0]
	v_mfma_scale_f32_16x16x128_f8f6f4 v[202:205], v[182:189], v[214:221], 0, v149, v149 op_sel_hi:[0,0,0]
	s_setprio 0
	s_barrier
	s_add_i32 s74, s9, s47
	s_mov_b32 m0, s74
	ds_read_b128 v[64:67], v131 offset:16384
	ds_read_b128 v[68:71], v131 offset:17408
	ds_read_b128 v[72:75], v131 offset:18432
	ds_read_b128 v[76:79], v131 offset:19456
	ds_read_b128 v[80:83], v131 offset:20480
	ds_read_b128 v[84:87], v131 offset:21504
	ds_read_b128 v[88:91], v131 offset:22528
	ds_read_b128 v[92:95], v131 offset:23552
	global_load_lds_dwordx4 v130, s[44:45]
	s_add_i32 m0, s74, 0x2000
	s_nop 0
	global_load_lds_dwordx4 v132, s[44:45]
	s_add_u32 s44, s44, 0x20000
	s_addc_u32 s45, s45, 0
	s_add_i32 s74, s11, s47
	s_mov_b32 m0, s74
	s_nop 0
	global_load_lds_dwordx4 v130, s[44:45]
	s_add_i32 m0, s74, 0x2000
	s_nop 0
	global_load_lds_dwordx4 v132, s[44:45]
	ds_read_b32 v20, v143
	ds_read_b32 v21, v145
	s_mov_b32 m0, s52
	s_waitcnt lgkmcnt(0)
	v_add_u32_e32 v20, v20, v146
	v_add_u32_e32 v21, v21, v146
	v_cndmask_b32_e32 v20, v142, v20, vcc
	v_cndmask_b32_e32 v21, v144, v21, vcc
	global_load_lds_dwordx4 v20, s[42:43]
	s_mov_b32 m0, s53
	s_nop 0
	global_load_lds_dwordx4 v21, s[42:43]
	s_waitcnt vmcnt(8)
	s_waitcnt lgkmcnt(0)
	s_barrier
	s_setprio 1
	v_mfma_scale_f32_16x16x128_f8f6f4 v[56:59], v[152:159], v[64:71], 0, v149, v149 op_sel_hi:[0,0,0]
	v_mfma_scale_f32_16x16x128_f8f6f4 v[234:237], v[166:173], v[80:87], 0, v149, v149 op_sel_hi:[0,0,0]
	v_mfma_scale_f32_16x16x128_f8f6f4 v[8:11], v[152:159], v[88:95], 0, v149, v149 op_sel_hi:[0,0,0]
	v_mfma_scale_f32_16x16x128_f8f6f4 v[206:209], v[166:173], v[64:71], 0, v149, v149 op_sel_hi:[0,0,0]
	v_mfma_scale_f32_16x16x128_f8f6f4 v[210:213], v[152:159], v[72:79], 0, v149, v149 op_sel_hi:[0,0,0]
	v_mfma_scale_f32_16x16x128_f8f6f4 v[214:217], v[166:173], v[72:79], 0, v149, v149 op_sel_hi:[0,0,0]
	v_mfma_scale_f32_16x16x128_f8f6f4 v[218:221], v[152:159], v[80:87], 0, v149, v149 op_sel_hi:[0,0,0]
	v_mfma_scale_f32_16x16x128_f8f6f4 v[238:241], v[166:173], v[88:95], 0, v149, v149 op_sel_hi:[0,0,0]
	s_setprio 0
	s_setprio 1
	v_mfma_scale_f32_16x16x128_f8f6f4 v[60:63], v[174:181], v[64:71], 0, v149, v149 op_sel_hi:[0,0,0]
	v_mfma_scale_f32_16x16x128_f8f6f4 v[52:55], v[182:189], v[64:71], 0, v149, v149 op_sel_hi:[0,0,0]
	v_mfma_scale_f32_16x16x128_f8f6f4 v[242:245], v[174:181], v[72:79], 0, v149, v149 op_sel_hi:[0,0,0]
	v_mfma_scale_f32_16x16x128_f8f6f4 v[246:249], v[182:189], v[72:79], 0, v149, v149 op_sel_hi:[0,0,0]
	v_mfma_scale_f32_16x16x128_f8f6f4 v[250:253], v[174:181], v[80:87], 0, v149, v149 op_sel_hi:[0,0,0]
	v_mfma_scale_f32_16x16x128_f8f6f4 v[136:139], v[182:189], v[80:87], 0, v149, v149 op_sel_hi:[0,0,0]
	v_mfma_scale_f32_16x16x128_f8f6f4 v[68:71], v[174:181], v[88:95], 0, v149, v149 op_sel_hi:[0,0,0]
	v_mfma_scale_f32_16x16x128_f8f6f4 v[64:67], v[182:189], v[88:95], 0, v149, v149 op_sel_hi:[0,0,0]
	s_setprio 0
	s_barrier
	s_add_i32 s44, 0, 0x18000
	s_add_i32 s45, 0, 0x1c000
	s_nop 0
	v_add_u32_e32 v16, s44, v133
	v_add_u32_e32 v20, s45, v133
	ds_read_b128 v[0:3], v16
	ds_read_b128 v[4:7], v16 offset:1024
	ds_read_b128 v[12:15], v16 offset:2048
	ds_read_b128 v[16:19], v16 offset:3072
	ds_read_b128 v[152:155], v20
	ds_read_b128 v[156:159], v20 offset:1024
	ds_read_b128 v[166:169], v20 offset:2048
	ds_read_b128 v[170:173], v20 offset:3072
	ds_read_b128 v[24:27], v131 offset:33792
	ds_read_b128 v[28:31], v131 offset:34816
	ds_read_b128 v[32:35], v131 offset:35840
	ds_read_b128 v[36:39], v131 offset:36864
	ds_read_b128 v[20:23], v131 offset:32768
	ds_read_b32 v72, v143 offset:512
	ds_read_b32 v73, v145 offset:512
	ds_read_b128 v[40:43], v131 offset:37888
	ds_read_b128 v[44:47], v131 offset:38912
	ds_read_b128 v[48:51], v131 offset:39936
	s_waitcnt lgkmcnt(0)
	v_add_u32_e32 v72, v72, v146
	s_mov_b32 m0, s54
	v_add_u32_e32 v73, v73, v146
	v_cndmask_b32_e32 v72, v141, v72, vcc
	v_cndmask_b32_e32 v73, v151, v73, vcc
	global_load_lds_dwordx4 v72, s[42:43]
	s_mov_b32 m0, s55
	s_nop 0
	global_load_lds_dwordx4 v73, s[42:43]
	s_waitcnt vmcnt(8)
	s_waitcnt lgkmcnt(0)
	s_barrier
	s_setprio 1
	v_mfma_scale_f32_16x16x128_f8f6f4 v[120:123], v[0:7], v[20:27], v[120:123], v149, v149 op_sel_hi:[0,0,0]
	v_mfma_scale_f32_16x16x128_f8f6f4 v[112:115], v[12:19], v[20:27], v[112:115], v149, v149 op_sel_hi:[0,0,0]
	v_mfma_scale_f32_16x16x128_f8f6f4 v[104:107], v[0:7], v[28:35], v[104:107], v149, v149 op_sel_hi:[0,0,0]
	v_mfma_scale_f32_16x16x128_f8f6f4 v[96:99], v[12:19], v[28:35], v[96:99], v149, v149 op_sel_hi:[0,0,0]
	v_mfma_scale_f32_16x16x128_f8f6f4 v[88:91], v[0:7], v[36:43], v[160:163], v149, v149 op_sel_hi:[0,0,0]
	v_mfma_scale_f32_16x16x128_f8f6f4 v[80:83], v[12:19], v[36:43], v[222:225], v149, v149 op_sel_hi:[0,0,0]
	v_mfma_scale_f32_16x16x128_f8f6f4 v[72:75], v[0:7], v[44:51], v[226:229], v149, v149 op_sel_hi:[0,0,0]
	v_mfma_scale_f32_16x16x128_f8f6f4 v[230:233], v[12:19], v[44:51], v[230:233], v149, v149 op_sel_hi:[0,0,0]
	s_setprio 0
	s_setprio 1
	v_mfma_scale_f32_16x16x128_f8f6f4 v[124:127], v[152:159], v[20:27], v[124:127], v149, v149 op_sel_hi:[0,0,0]
	v_mfma_scale_f32_16x16x128_f8f6f4 v[116:119], v[166:173], v[20:27], v[116:119], v149, v149 op_sel_hi:[0,0,0]
	v_mfma_scale_f32_16x16x128_f8f6f4 v[108:111], v[152:159], v[28:35], v[108:111], v149, v149 op_sel_hi:[0,0,0]
	v_mfma_scale_f32_16x16x128_f8f6f4 v[100:103], v[166:173], v[28:35], v[100:103], v149, v149 op_sel_hi:[0,0,0]
	v_mfma_scale_f32_16x16x128_f8f6f4 v[92:95], v[152:159], v[36:43], v[190:193], v149, v149 op_sel_hi:[0,0,0]
	v_mfma_scale_f32_16x16x128_f8f6f4 v[84:87], v[166:173], v[36:43], v[194:197], v149, v149 op_sel_hi:[0,0,0]
	v_mfma_scale_f32_16x16x128_f8f6f4 v[76:79], v[152:159], v[44:51], v[198:201], v149, v149 op_sel_hi:[0,0,0]
	v_mfma_scale_f32_16x16x128_f8f6f4 v[20:23], v[166:173], v[44:51], v[202:205], v149, v149 op_sel_hi:[0,0,0]
	s_setprio 0
	s_barrier
	s_add_i32 s42, s44, s47
	s_mov_b32 m0, s42
	ds_read_b128 v[174:177], v131 offset:49152
	ds_read_b128 v[178:181], v131 offset:50176
	ds_read_b128 v[182:185], v131 offset:51200
	ds_read_b128 v[186:189], v131 offset:52224
	ds_read_b128 v[190:193], v131 offset:53248
	ds_read_b128 v[194:197], v131 offset:54272
	ds_read_b128 v[198:201], v131 offset:55296
	ds_read_b128 v[202:205], v131 offset:56320
	global_load_lds_dwordx4 v130, s[38:39]
	s_add_i32 m0, s42, 0x2000
	s_nop 0
	global_load_lds_dwordx4 v132, s[38:39]
	s_add_u32 s38, s38, 0x20000
	s_addc_u32 s39, s39, 0
	s_add_i32 s42, s45, s47
	s_mov_b32 m0, s42
	s_nop 0
	global_load_lds_dwordx4 v130, s[38:39]
	s_add_i32 m0, s42, 0x2000
	s_nop 0
	global_load_lds_dwordx4 v132, s[38:39]
	ds_read_b32 v24, v143
	ds_read_b32 v25, v145
	s_mov_b32 m0, s63
	s_waitcnt lgkmcnt(0)
	v_add_u32_e32 v24, v24, v146
	v_add_u32_e32 v25, v25, v146
	v_cndmask_b32_e32 v24, v142, v24, vcc
	v_cndmask_b32_e32 v25, v144, v25, vcc
	global_load_lds_dwordx4 v24, s[40:41]
	s_mov_b32 m0, s64
	s_nop 0
	global_load_lds_dwordx4 v25, s[40:41]
	s_waitcnt vmcnt(8)
	s_waitcnt lgkmcnt(0)
	s_barrier
	s_setprio 1
	v_mfma_scale_f32_16x16x128_f8f6f4 v[56:59], v[0:7], v[174:181], v[56:59], v149, v149 op_sel_hi:[0,0,0]
	v_mfma_scale_f32_16x16x128_f8f6f4 v[48:51], v[12:19], v[174:181], v[206:209], v149, v149 op_sel_hi:[0,0,0]
	v_mfma_scale_f32_16x16x128_f8f6f4 v[40:43], v[0:7], v[182:189], v[210:213], v149, v149 op_sel_hi:[0,0,0]
	v_mfma_scale_f32_16x16x128_f8f6f4 v[32:35], v[12:19], v[182:189], v[214:217], v149, v149 op_sel_hi:[0,0,0]
	v_mfma_scale_f32_16x16x128_f8f6f4 v[24:27], v[0:7], v[190:197], v[218:221], v149, v149 op_sel_hi:[0,0,0]
	v_mfma_scale_f32_16x16x128_f8f6f4 v[234:237], v[12:19], v[190:197], v[234:237], v149, v149 op_sel_hi:[0,0,0]
	v_mfma_scale_f32_16x16x128_f8f6f4 v[8:11], v[0:7], v[198:205], v[8:11], v149, v149 op_sel_hi:[0,0,0]
	v_mfma_scale_f32_16x16x128_f8f6f4 v[0:3], v[12:19], v[198:205], v[238:241], v149, v149 op_sel_hi:[0,0,0]
	s_setprio 0
	s_setprio 1
	v_mfma_scale_f32_16x16x128_f8f6f4 v[60:63], v[152:159], v[174:181], v[60:63], v149, v149 op_sel_hi:[0,0,0]
	v_mfma_scale_f32_16x16x128_f8f6f4 v[52:55], v[166:173], v[174:181], v[52:55], v149, v149 op_sel_hi:[0,0,0]
	v_mfma_scale_f32_16x16x128_f8f6f4 v[44:47], v[152:159], v[182:189], v[242:245], v149, v149 op_sel_hi:[0,0,0]
	v_mfma_scale_f32_16x16x128_f8f6f4 v[36:39], v[166:173], v[182:189], v[246:249], v149, v149 op_sel_hi:[0,0,0]
	v_mfma_scale_f32_16x16x128_f8f6f4 v[28:31], v[152:159], v[190:197], v[250:253], v149, v149 op_sel_hi:[0,0,0]
	v_mfma_scale_f32_16x16x128_f8f6f4 v[16:19], v[166:173], v[190:197], v[136:139], v149, v149 op_sel_hi:[0,0,0]
	v_mfma_scale_f32_16x16x128_f8f6f4 v[12:15], v[152:159], v[198:205], v[68:71], v149, v149 op_sel_hi:[0,0,0]
	v_mfma_scale_f32_16x16x128_f8f6f4 v[4:7], v[166:173], v[198:205], v[64:67], v149, v149 op_sel_hi:[0,0,0]
	s_setprio 0
	s_barrier
	s_add_i32 s29, s29, 2
	s_add_u32 s21, s21, 0x100
	s_addc_u32 s27, s27, 0
	s_add_u32 s30, s30, 0x100
	s_addc_u32 s31, s31, 0
	s_cmp_gt_u32 s29, 5

.LBB0_961:
	s_ashr_i32 s27, s26, 31
	s_lshl_b64 s[26:27], s[26:27], 19
	s_add_u32 s21, s57, s26
	s_addc_u32 s30, s58, s27
	s_ashr_i32 s29, s28, 31
	s_lshl_b64 s[26:27], s[28:29], 7
	s_add_u32 s21, s21, s26
	s_addc_u32 s27, s30, s27
	s_add_u32 s26, s21, s59
	s_addc_u32 s27, s27, 0
	s_mov_b32 s98, 0x44800000
	s_mov_b32 s99, 0x44800000
	v_pk_mul_f32 v[64:65], v[120:121], s[10:11] op_sel_hi:[1,0]
	v_pk_mul_f32 v[66:67], v[122:123], s[10:11] op_sel_hi:[1,0]
	v_pk_mul_f32 v[68:69], v[112:113], s[10:11] op_sel_hi:[1,0]
	v_pk_mul_f32 v[70:71], v[114:115], s[10:11] op_sel_hi:[1,0]
	v_exp_f32_e32 v64, v64
	v_exp_f32_e32 v65, v65
	v_exp_f32_e32 v66, v66
	v_exp_f32_e32 v67, v67
	v_exp_f32_e32 v68, v68
	v_exp_f32_e32 v69, v69
	v_exp_f32_e32 v70, v70
	v_exp_f32_e32 v71, v71
	v_pk_fma_f32 v[64:65], v[64:65], s[98:99], s[98:99]
	v_pk_fma_f32 v[66:67], v[66:67], s[98:99], s[98:99]
	v_pk_fma_f32 v[68:69], v[68:69], s[98:99], s[98:99]
	v_pk_fma_f32 v[70:71], v[70:71], s[98:99], s[98:99]
	v_rcp_f32_e32 v64, v64
	v_rcp_f32_e32 v65, v65
	v_pk_mul_f32 v[120:121], v[120:121], v[124:125]
	v_rcp_f32_e32 v66, v66
	v_rcp_f32_e32 v67, v67
	v_pk_mul_f32 v[122:123], v[122:123], v[126:127]
	v_rcp_f32_e32 v68, v68
	v_rcp_f32_e32 v69, v69
	v_pk_mul_f32 v[112:113], v[112:113], v[116:117]
	v_rcp_f32_e32 v70, v70
	v_rcp_f32_e32 v71, v71
	v_pk_mul_f32 v[114:115], v[114:115], v[118:119]
	v_add_u32_e32 v124, v128, v134
	v_pk_mul_f32 v[120:121], v[120:121], v[64:65]
	v_pk_mul_f32 v[122:123], v[122:123], v[66:67]
	v_pk_mul_f32 v[112:113], v[112:113], v[68:69]
	v_pk_mul_f32 v[114:115], v[114:115], v[70:71]
	v_med3_f32 v120, v120, s68, v150
	v_med3_f32 v121, v121, s68, v150
	v_med3_f32 v122, v122, s68, v150
	v_med3_f32 v123, v123, s68, v150
	v_med3_f32 v112, v112, s68, v150
	v_med3_f32 v113, v113, s68, v150
	v_med3_f32 v114, v114, s68, v150
	v_med3_f32 v115, v115, s68, v150
	v_cvt_pk_fp8_f32 v136, v120, v121
	v_cvt_pk_fp8_f32 v137, v112, v113
	v_cvt_pk_fp8_f32 v136, v122, v123 op_sel:[0,0,1]
	v_cvt_pk_fp8_f32 v137, v114, v115 op_sel:[0,0,1]
	s_mov_b32 s100, s26
	s_mov_b32 s101, s27
	global_store_dwordx2 v124, v[136:137], s[100:101] nt
	v_pk_mul_f32 v[64:65], v[104:105], s[10:11] op_sel_hi:[1,0]
	v_pk_mul_f32 v[66:67], v[106:107], s[10:11] op_sel_hi:[1,0]
	v_pk_mul_f32 v[68:69], v[96:97], s[10:11] op_sel_hi:[1,0]
	v_pk_mul_f32 v[70:71], v[98:99], s[10:11] op_sel_hi:[1,0]
	v_exp_f32_e32 v64, v64
	v_exp_f32_e32 v65, v65
	v_exp_f32_e32 v66, v66
	v_exp_f32_e32 v67, v67
	v_exp_f32_e32 v68, v68
	v_exp_f32_e32 v69, v69
	v_exp_f32_e32 v70, v70
	v_exp_f32_e32 v71, v71
	v_pk_fma_f32 v[64:65], v[64:65], s[98:99], s[98:99]
	v_pk_fma_f32 v[66:67], v[66:67], s[98:99], s[98:99]
	v_pk_fma_f32 v[68:69], v[68:69], s[98:99], s[98:99]
	v_pk_fma_f32 v[70:71], v[70:71], s[98:99], s[98:99]
	v_rcp_f32_e32 v64, v64
	v_rcp_f32_e32 v65, v65
	v_pk_mul_f32 v[104:105], v[104:105], v[108:109]
	v_rcp_f32_e32 v66, v66
	v_rcp_f32_e32 v67, v67
	v_pk_mul_f32 v[106:107], v[106:107], v[110:111]
	v_rcp_f32_e32 v68, v68
	v_rcp_f32_e32 v69, v69
	v_pk_mul_f32 v[96:97], v[96:97], v[100:101]
	v_rcp_f32_e32 v70, v70
	v_rcp_f32_e32 v71, v71
	v_pk_mul_f32 v[98:99], v[98:99], v[102:103]
	v_pk_mul_f32 v[104:105], v[104:105], v[64:65]
	v_pk_mul_f32 v[106:107], v[106:107], v[66:67]
	v_pk_mul_f32 v[96:97], v[96:97], v[68:69]
	v_pk_mul_f32 v[98:99], v[98:99], v[70:71]
	v_med3_f32 v104, v104, s68, v150
	v_med3_f32 v105, v105, s68, v150
	v_med3_f32 v106, v106, s68, v150
	v_med3_f32 v107, v107, s68, v150
	v_med3_f32 v96, v96, s68, v150
	v_med3_f32 v97, v97, s68, v150
	v_med3_f32 v98, v98, s68, v150
	v_med3_f32 v99, v99, s68, v150
	v_cvt_pk_fp8_f32 v140, v104, v105
	v_cvt_pk_fp8_f32 v141, v96, v97
	v_cvt_pk_fp8_f32 v140, v106, v107 op_sel:[0,0,1]
	v_cvt_pk_fp8_f32 v141, v98, v99 op_sel:[0,0,1]
	s_add_u32 s100, s26, 0x8000
	s_addc_u32 s101, s27, 0
	global_store_dwordx2 v124, v[140:141], s[100:101] nt
	v_pk_mul_f32 v[64:65], v[88:89], s[10:11] op_sel_hi:[1,0]
	v_pk_mul_f32 v[66:67], v[90:91], s[10:11] op_sel_hi:[1,0]
	v_pk_mul_f32 v[68:69], v[80:81], s[10:11] op_sel_hi:[1,0]
	v_pk_mul_f32 v[70:71], v[82:83], s[10:11] op_sel_hi:[1,0]
	v_exp_f32_e32 v64, v64
	v_exp_f32_e32 v65, v65
	v_exp_f32_e32 v66, v66
	v_exp_f32_e32 v67, v67
	v_exp_f32_e32 v68, v68
	v_exp_f32_e32 v69, v69
	v_exp_f32_e32 v70, v70
	v_exp_f32_e32 v71, v71
	v_pk_fma_f32 v[64:65], v[64:65], s[98:99], s[98:99]
	v_pk_fma_f32 v[66:67], v[66:67], s[98:99], s[98:99]
	v_pk_fma_f32 v[68:69], v[68:69], s[98:99], s[98:99]
	v_pk_fma_f32 v[70:71], v[70:71], s[98:99], s[98:99]
	v_rcp_f32_e32 v64, v64
	v_rcp_f32_e32 v65, v65
	v_pk_mul_f32 v[88:89], v[88:89], v[92:93]
	v_rcp_f32_e32 v66, v66
	v_rcp_f32_e32 v67, v67
	v_pk_mul_f32 v[90:91], v[90:91], v[94:95]
	v_rcp_f32_e32 v68, v68
	v_rcp_f32_e32 v69, v69
	v_pk_mul_f32 v[80:81], v[80:81], v[84:85]
	v_rcp_f32_e32 v70, v70
	v_rcp_f32_e32 v71, v71
	v_pk_mul_f32 v[82:83], v[82:83], v[86:87]
	v_pk_mul_f32 v[88:89], v[88:89], v[64:65]
	v_pk_mul_f32 v[90:91], v[90:91], v[66:67]
	v_pk_mul_f32 v[80:81], v[80:81], v[68:69]
	v_pk_mul_f32 v[82:83], v[82:83], v[70:71]
	v_med3_f32 v88, v88, s68, v150
	v_med3_f32 v89, v89, s68, v150
	v_med3_f32 v90, v90, s68, v150
	v_med3_f32 v91, v91, s68, v150
	v_med3_f32 v80, v80, s68, v150
	v_med3_f32 v81, v81, s68, v150
	v_med3_f32 v82, v82, s68, v150
	v_med3_f32 v83, v83, s68, v150
	v_cvt_pk_fp8_f32 v136, v88, v89
	v_cvt_pk_fp8_f32 v137, v80, v81
	v_cvt_pk_fp8_f32 v136, v90, v91 op_sel:[0,0,1]
	v_cvt_pk_fp8_f32 v137, v82, v83 op_sel:[0,0,1]
	s_add_u32 s100, s26, 0x10000
	s_addc_u32 s101, s27, 0
	global_store_dwordx2 v124, v[136:137], s[100:101] nt
	v_pk_mul_f32 v[64:65], v[72:73], s[10:11] op_sel_hi:[1,0]
	v_pk_mul_f32 v[66:67], v[74:75], s[10:11] op_sel_hi:[1,0]
	v_pk_mul_f32 v[68:69], v[230:231], s[10:11] op_sel_hi:[1,0]
	v_pk_mul_f32 v[70:71], v[232:233], s[10:11] op_sel_hi:[1,0]
	v_exp_f32_e32 v64, v64
	v_exp_f32_e32 v65, v65
	v_exp_f32_e32 v66, v66
	v_exp_f32_e32 v67, v67
	v_exp_f32_e32 v68, v68
	v_exp_f32_e32 v69, v69
	v_exp_f32_e32 v70, v70
	v_exp_f32_e32 v71, v71
	v_pk_fma_f32 v[64:65], v[64:65], s[98:99], s[98:99]
	v_pk_fma_f32 v[66:67], v[66:67], s[98:99], s[98:99]
	v_pk_fma_f32 v[68:69], v[68:69], s[98:99], s[98:99]
	v_pk_fma_f32 v[70:71], v[70:71], s[98:99], s[98:99]
	v_rcp_f32_e32 v64, v64
	v_rcp_f32_e32 v65, v65
	v_pk_mul_f32 v[72:73], v[72:73], v[76:77]
	v_rcp_f32_e32 v66, v66
	v_rcp_f32_e32 v67, v67
	v_pk_mul_f32 v[74:75], v[74:75], v[78:79]
	v_rcp_f32_e32 v68, v68
	v_rcp_f32_e32 v69, v69
	v_pk_mul_f32 v[230:231], v[230:231], v[20:21]
	v_rcp_f32_e32 v70, v70
	v_rcp_f32_e32 v71, v71
	v_pk_mul_f32 v[232:233], v[232:233], v[22:23]
	v_pk_mul_f32 v[72:73], v[72:73], v[64:65]
	v_pk_mul_f32 v[74:75], v[74:75], v[66:67]
	v_pk_mul_f32 v[230:231], v[230:231], v[68:69]
	v_pk_mul_f32 v[232:233], v[232:233], v[70:71]
	v_med3_f32 v72, v72, s68, v150
	v_med3_f32 v73, v73, s68, v150
	v_med3_f32 v74, v74, s68, v150
	v_med3_f32 v75, v75, s68, v150
	v_med3_f32 v230, v230, s68, v150
	v_med3_f32 v231, v231, s68, v150
	v_med3_f32 v232, v232, s68, v150
	v_med3_f32 v233, v233, s68, v150
	v_cvt_pk_fp8_f32 v140, v72, v73
	v_cvt_pk_fp8_f32 v141, v230, v231
	v_cvt_pk_fp8_f32 v140, v74, v75 op_sel:[0,0,1]
	v_cvt_pk_fp8_f32 v141, v232, v233 op_sel:[0,0,1]
	s_add_u32 s100, s26, 0x18000
	s_addc_u32 s101, s27, 0
	global_store_dwordx2 v124, v[140:141], s[100:101] nt
	v_pk_mul_f32 v[64:65], v[56:57], s[10:11] op_sel_hi:[1,0]
	v_pk_mul_f32 v[66:67], v[58:59], s[10:11] op_sel_hi:[1,0]
	v_pk_mul_f32 v[68:69], v[48:49], s[10:11] op_sel_hi:[1,0]
	v_pk_mul_f32 v[70:71], v[50:51], s[10:11] op_sel_hi:[1,0]
	v_exp_f32_e32 v64, v64
	v_exp_f32_e32 v65, v65
	v_exp_f32_e32 v66, v66
	v_exp_f32_e32 v67, v67
	v_exp_f32_e32 v68, v68
	v_exp_f32_e32 v69, v69
	v_exp_f32_e32 v70, v70
	v_exp_f32_e32 v71, v71
	v_pk_fma_f32 v[64:65], v[64:65], s[98:99], s[98:99]
	v_pk_fma_f32 v[66:67], v[66:67], s[98:99], s[98:99]
	v_pk_fma_f32 v[68:69], v[68:69], s[98:99], s[98:99]
	v_pk_fma_f32 v[70:71], v[70:71], s[98:99], s[98:99]
	v_rcp_f32_e32 v64, v64
	v_rcp_f32_e32 v65, v65
	v_pk_mul_f32 v[56:57], v[56:57], v[60:61]
	v_rcp_f32_e32 v66, v66
	v_rcp_f32_e32 v67, v67
	v_pk_mul_f32 v[58:59], v[58:59], v[62:63]
	v_rcp_f32_e32 v68, v68
	v_rcp_f32_e32 v69, v69
	v_pk_mul_f32 v[48:49], v[48:49], v[52:53]
	v_rcp_f32_e32 v70, v70
	v_rcp_f32_e32 v71, v71
	v_pk_mul_f32 v[50:51], v[50:51], v[54:55]
	v_pk_mul_f32 v[56:57], v[56:57], v[64:65]
	v_pk_mul_f32 v[58:59], v[58:59], v[66:67]
	v_pk_mul_f32 v[48:49], v[48:49], v[68:69]
	v_pk_mul_f32 v[50:51], v[50:51], v[70:71]
	v_med3_f32 v56, v56, s68, v150
	v_med3_f32 v57, v57, s68, v150
	v_med3_f32 v58, v58, s68, v150
	v_med3_f32 v59, v59, s68, v150
	v_med3_f32 v48, v48, s68, v150
	v_med3_f32 v49, v49, s68, v150
	v_med3_f32 v50, v50, s68, v150
	v_med3_f32 v51, v51, s68, v150
	v_cvt_pk_fp8_f32 v136, v56, v57
	v_cvt_pk_fp8_f32 v137, v48, v49
	v_cvt_pk_fp8_f32 v136, v58, v59 op_sel:[0,0,1]
	v_cvt_pk_fp8_f32 v137, v50, v51 op_sel:[0,0,1]
	s_add_u32 s100, s26, 0x40000
	s_addc_u32 s101, s27, 0
	global_store_dwordx2 v124, v[136:137], s[100:101] nt
	v_pk_mul_f32 v[64:65], v[40:41], s[10:11] op_sel_hi:[1,0]
	v_pk_mul_f32 v[66:67], v[42:43], s[10:11] op_sel_hi:[1,0]
	v_pk_mul_f32 v[68:69], v[32:33], s[10:11] op_sel_hi:[1,0]
	v_pk_mul_f32 v[70:71], v[34:35], s[10:11] op_sel_hi:[1,0]
	v_exp_f32_e32 v64, v64
	v_exp_f32_e32 v65, v65
	v_exp_f32_e32 v66, v66
	v_exp_f32_e32 v67, v67
	v_exp_f32_e32 v68, v68
	v_exp_f32_e32 v69, v69
	v_exp_f32_e32 v70, v70
	v_exp_f32_e32 v71, v71
	v_pk_fma_f32 v[64:65], v[64:65], s[98:99], s[98:99]
	v_pk_fma_f32 v[66:67], v[66:67], s[98:99], s[98:99]
	v_pk_fma_f32 v[68:69], v[68:69], s[98:99], s[98:99]
	v_pk_fma_f32 v[70:71], v[70:71], s[98:99], s[98:99]
	v_rcp_f32_e32 v64, v64
	v_rcp_f32_e32 v65, v65
	v_pk_mul_f32 v[40:41], v[40:41], v[44:45]
	v_rcp_f32_e32 v66, v66
	v_rcp_f32_e32 v67, v67
	v_pk_mul_f32 v[42:43], v[42:43], v[46:47]
	v_rcp_f32_e32 v68, v68
	v_rcp_f32_e32 v69, v69
	v_pk_mul_f32 v[32:33], v[32:33], v[36:37]
	v_rcp_f32_e32 v70, v70
	v_rcp_f32_e32 v71, v71
	v_pk_mul_f32 v[34:35], v[34:35], v[38:39]
	v_pk_mul_f32 v[40:41], v[40:41], v[64:65]
	v_pk_mul_f32 v[42:43], v[42:43], v[66:67]
	v_pk_mul_f32 v[32:33], v[32:33], v[68:69]
	v_pk_mul_f32 v[34:35], v[34:35], v[70:71]
	v_med3_f32 v40, v40, s68, v150
	v_med3_f32 v41, v41, s68, v150
	v_med3_f32 v42, v42, s68, v150
	v_med3_f32 v43, v43, s68, v150
	v_med3_f32 v32, v32, s68, v150
	v_med3_f32 v33, v33, s68, v150
	v_med3_f32 v34, v34, s68, v150
	v_med3_f32 v35, v35, s68, v150
	v_cvt_pk_fp8_f32 v140, v40, v41
	v_cvt_pk_fp8_f32 v141, v32, v33
	v_cvt_pk_fp8_f32 v140, v42, v43 op_sel:[0,0,1]
	v_cvt_pk_fp8_f32 v141, v34, v35 op_sel:[0,0,1]
	s_add_u32 s100, s26, 0x48000
	s_addc_u32 s101, s27, 0
	global_store_dwordx2 v124, v[140:141], s[100:101] nt
	v_pk_mul_f32 v[64:65], v[24:25], s[10:11] op_sel_hi:[1,0]
	v_pk_mul_f32 v[66:67], v[26:27], s[10:11] op_sel_hi:[1,0]
	v_pk_mul_f32 v[68:69], v[234:235], s[10:11] op_sel_hi:[1,0]
	v_pk_mul_f32 v[70:71], v[236:237], s[10:11] op_sel_hi:[1,0]
	v_exp_f32_e32 v64, v64
	v_exp_f32_e32 v65, v65
	v_exp_f32_e32 v66, v66
	v_exp_f32_e32 v67, v67
	v_exp_f32_e32 v68, v68
	v_exp_f32_e32 v69, v69
	v_exp_f32_e32 v70, v70
	v_exp_f32_e32 v71, v71
	v_pk_fma_f32 v[64:65], v[64:65], s[98:99], s[98:99]
	v_pk_fma_f32 v[66:67], v[66:67], s[98:99], s[98:99]
	v_pk_fma_f32 v[68:69], v[68:69], s[98:99], s[98:99]
	v_pk_fma_f32 v[70:71], v[70:71], s[98:99], s[98:99]
	v_rcp_f32_e32 v64, v64
	v_rcp_f32_e32 v65, v65
	v_pk_mul_f32 v[24:25], v[24:25], v[28:29]
	v_rcp_f32_e32 v66, v66
	v_rcp_f32_e32 v67, v67
	v_pk_mul_f32 v[26:27], v[26:27], v[30:31]
	v_rcp_f32_e32 v68, v68
	v_rcp_f32_e32 v69, v69
	v_pk_mul_f32 v[234:235], v[234:235], v[16:17]
	v_rcp_f32_e32 v70, v70
	v_rcp_f32_e32 v71, v71
	v_pk_mul_f32 v[236:237], v[236:237], v[18:19]
	v_pk_mul_f32 v[24:25], v[24:25], v[64:65]
	v_pk_mul_f32 v[26:27], v[26:27], v[66:67]
	v_pk_mul_f32 v[234:235], v[234:235], v[68:69]
	v_pk_mul_f32 v[236:237], v[236:237], v[70:71]
	v_med3_f32 v24, v24, s68, v150
	v_med3_f32 v25, v25, s68, v150
	v_med3_f32 v26, v26, s68, v150
	v_med3_f32 v27, v27, s68, v150
	v_med3_f32 v234, v234, s68, v150
	v_med3_f32 v235, v235, s68, v150
	v_med3_f32 v236, v236, s68, v150
	v_med3_f32 v237, v237, s68, v150
	v_cvt_pk_fp8_f32 v136, v24, v25
	v_cvt_pk_fp8_f32 v137, v234, v235
	v_cvt_pk_fp8_f32 v136, v26, v27 op_sel:[0,0,1]
	v_cvt_pk_fp8_f32 v137, v236, v237 op_sel:[0,0,1]
	s_add_u32 s100, s26, 0x50000
	s_addc_u32 s101, s27, 0
	global_store_dwordx2 v124, v[136:137], s[100:101] nt
	v_pk_mul_f32 v[64:65], v[8:9], s[10:11] op_sel_hi:[1,0]
	v_pk_mul_f32 v[66:67], v[10:11], s[10:11] op_sel_hi:[1,0]
	v_pk_mul_f32 v[68:69], v[0:1], s[10:11] op_sel_hi:[1,0]
	v_pk_mul_f32 v[70:71], v[2:3], s[10:11] op_sel_hi:[1,0]
	v_exp_f32_e32 v64, v64
	v_exp_f32_e32 v65, v65
	v_exp_f32_e32 v66, v66
	v_exp_f32_e32 v67, v67
	v_exp_f32_e32 v68, v68
	v_exp_f32_e32 v69, v69
	v_exp_f32_e32 v70, v70
	v_exp_f32_e32 v71, v71
	v_pk_fma_f32 v[64:65], v[64:65], s[98:99], s[98:99]
	v_pk_fma_f32 v[66:67], v[66:67], s[98:99], s[98:99]
	v_pk_fma_f32 v[68:69], v[68:69], s[98:99], s[98:99]
	v_pk_fma_f32 v[70:71], v[70:71], s[98:99], s[98:99]
	v_rcp_f32_e32 v64, v64
	v_rcp_f32_e32 v65, v65
	v_pk_mul_f32 v[8:9], v[8:9], v[12:13]
	v_rcp_f32_e32 v66, v66
	v_rcp_f32_e32 v67, v67
	v_pk_mul_f32 v[10:11], v[10:11], v[14:15]
	v_rcp_f32_e32 v68, v68
	v_rcp_f32_e32 v69, v69
	v_pk_mul_f32 v[0:1], v[0:1], v[4:5]
	v_rcp_f32_e32 v70, v70
	v_rcp_f32_e32 v71, v71
	v_pk_mul_f32 v[2:3], v[2:3], v[6:7]
	v_pk_mul_f32 v[8:9], v[8:9], v[64:65]
	v_pk_mul_f32 v[10:11], v[10:11], v[66:67]
	v_pk_mul_f32 v[0:1], v[0:1], v[68:69]
	v_pk_mul_f32 v[2:3], v[2:3], v[70:71]
	v_med3_f32 v8, v8, s68, v150
	v_med3_f32 v9, v9, s68, v150
	v_med3_f32 v10, v10, s68, v150
	v_med3_f32 v11, v11, s68, v150
	v_med3_f32 v0, v0, s68, v150
	v_med3_f32 v1, v1, s68, v150
	v_med3_f32 v2, v2, s68, v150
	v_med3_f32 v3, v3, s68, v150
	v_cvt_pk_fp8_f32 v140, v8, v9
	v_cvt_pk_fp8_f32 v141, v0, v1
	v_cvt_pk_fp8_f32 v140, v10, v11 op_sel:[0,0,1]
	v_cvt_pk_fp8_f32 v141, v2, v3 op_sel:[0,0,1]
	s_add_u32 s100, s26, 0x58000
	s_addc_u32 s101, s27, 0
	global_store_dwordx2 v124, v[140:141], s[100:101] nt
	s_andn2_b64 vcc, exec, s[4:5]
	s_cbranch_vccnz .LBB0_964
	ds_read2st64_b32 v[142:143], v143 offset1:2
	ds_read2st64_b32 v[144:145], v145 offset1:2
	s_andn2_b64 vcc, exec, s[14:15]
	s_cbranch_vccnz .LBB0_953
	s_barrier
	s_branch .LBB0_953

.LBB0_1871:
	s_lshl_b32 s21, s8, 10
	s_add_i32 s21, s21, 0
	s_add_i32 s21, s21, 0x20000
	v_lshl_add_u32 v143, v147, 2, s21
	v_lshl_add_u32 v145, v148, 2, s21
	s_add_u32 s21, s30, 0x100
	s_addc_u32 s27, s31, 0
	s_add_u32 s30, s12, 0x80
	s_addc_u32 s31, s13, 0
	s_mov_b32 s29, -2
	s_add_u32 s42, s30, 0x80
	v_add_u32_e32 v64, s9, v133
	s_addc_u32 s43, s31, 0
	ds_read_b128 v[152:155], v64
	ds_read_b128 v[156:159], v64 offset:1024
	ds_read_b128 v[166:169], v64 offset:2048
	ds_read_b128 v[170:173], v64 offset:3072
	v_add_u32_e32 v64, s11, v133
	s_cmp_eq_u32 s29, 4
	ds_read_b128 v[174:177], v64
	ds_read_b128 v[178:181], v64 offset:1024
	ds_read_b128 v[182:185], v64 offset:2048
	ds_read_b128 v[186:189], v64 offset:3072
	s_cselect_b64 s[40:41], -1, 0
	s_and_b64 s[38:39], s[40:41], exec
	s_cselect_b32 s44, s22, s21
	s_cselect_b32 s43, s13, s43
	s_cselect_b32 s42, s12, s42
	s_cselect_b32 s45, s23, s27
	s_add_u32 s38, s44, 0x80
	s_addc_u32 s39, s45, 0
	s_and_b64 vcc, s[4:5], s[40:41]
	s_add_u32 s40, s42, 0x80
	s_addc_u32 s41, s43, 0
	s_add_i32 m0, s51, 0xc000
	ds_read_b128 v[190:193], v131
	ds_read_b128 v[194:197], v131 offset:1024
	ds_read_b128 v[198:201], v131 offset:2048
	ds_read_b128 v[202:205], v131 offset:3072
	ds_read_b128 v[206:209], v131 offset:4096
	ds_read_b128 v[210:213], v131 offset:5120
	ds_read_b128 v[214:217], v131 offset:6144
	ds_read_b128 v[218:221], v131 offset:7168
	global_load_lds_dwordx4 v141, s[30:31]
	s_add_i32 m0, s51, 0xe000
	s_nop 0
	global_load_lds_dwordx4 v151, s[30:31]
	s_waitcnt vmcnt(8)
	s_waitcnt lgkmcnt(0)
	s_barrier
	s_setprio 1
	s_waitcnt lgkmcnt(0)
	v_mfma_scale_f32_16x16x128_f8f6f4 v[120:123], v[152:159], v[190:197], 0, v149, v149 op_sel_hi:[0,0,0]
	v_mfma_scale_f32_16x16x128_f8f6f4 v[112:115], v[166:173], v[190:197], 0, v149, v149 op_sel_hi:[0,0,0]
	v_mfma_scale_f32_16x16x128_f8f6f4 v[104:107], v[152:159], v[198:205], 0, v149, v149 op_sel_hi:[0,0,0]
	v_mfma_scale_f32_16x16x128_f8f6f4 v[96:99], v[166:173], v[198:205], 0, v149, v149 op_sel_hi:[0,0,0]
	v_mfma_scale_f32_16x16x128_f8f6f4 v[230:233], v[166:173], v[214:221], 0, v149, v149 op_sel_hi:[0,0,0]
	v_mfma_scale_f32_16x16x128_f8f6f4 v[160:163], v[152:159], v[206:213], 0, v149, v149 op_sel_hi:[0,0,0]
	v_mfma_scale_f32_16x16x128_f8f6f4 v[222:225], v[166:173], v[206:213], 0, v149, v149 op_sel_hi:[0,0,0]
	v_mfma_scale_f32_16x16x128_f8f6f4 v[226:229], v[152:159], v[214:221], 0, v149, v149 op_sel_hi:[0,0,0]
	s_setprio 0
	s_setprio 1
	v_mfma_scale_f32_16x16x128_f8f6f4 v[124:127], v[174:181], v[190:197], 0, v149, v149 op_sel_hi:[0,0,0]
	v_mfma_scale_f32_16x16x128_f8f6f4 v[116:119], v[182:189], v[190:197], 0, v149, v149 op_sel_hi:[0,0,0]
	v_mfma_scale_f32_16x16x128_f8f6f4 v[108:111], v[174:181], v[198:205], 0, v149, v149 op_sel_hi:[0,0,0]
	v_mfma_scale_f32_16x16x128_f8f6f4 v[100:103], v[182:189], v[198:205], 0, v149, v149 op_sel_hi:[0,0,0]
	v_mfma_scale_f32_16x16x128_f8f6f4 v[190:193], v[174:181], v[206:213], 0, v149, v149 op_sel_hi:[0,0,0]
	v_mfma_scale_f32_16x16x128_f8f6f4 v[194:197], v[182:189], v[206:213], 0, v149, v149 op_sel_hi:[0,0,0]
	v_mfma_scale_f32_16x16x128_f8f6f4 v[198:201], v[174:181], v[214:221], 0, v149, v149 op_sel_hi:[0,0,0]
	v_mfma_scale_f32_16x16x128_f8f6f4 v[202:205], v[182:189], v[214:221], 0, v149, v149 op_sel_hi:[0,0,0]
	s_setprio 0
	s_barrier
	s_add_i32 s73, s9, s46
	s_mov_b32 m0, s73
	ds_read_b128 v[64:67], v131 offset:16384
	ds_read_b128 v[68:71], v131 offset:17408
	ds_read_b128 v[72:75], v131 offset:18432
	ds_read_b128 v[76:79], v131 offset:19456
	ds_read_b128 v[80:83], v131 offset:20480
	ds_read_b128 v[84:87], v131 offset:21504
	ds_read_b128 v[88:91], v131 offset:22528
	ds_read_b128 v[92:95], v131 offset:23552
	global_load_lds_dwordx4 v130, s[44:45]
	s_add_i32 m0, s73, 0x2000
	s_nop 0
	global_load_lds_dwordx4 v132, s[44:45]
	s_add_u32 s44, s44, 0x20000
	s_addc_u32 s45, s45, 0
	s_add_i32 s73, s11, s46
	s_mov_b32 m0, s73
	s_nop 0
	global_load_lds_dwordx4 v130, s[44:45]
	s_add_i32 m0, s73, 0x2000
	s_nop 0
	global_load_lds_dwordx4 v132, s[44:45]
	ds_read_b32 v20, v143
	ds_read_b32 v21, v145
	s_mov_b32 m0, s51
	s_waitcnt lgkmcnt(0)
	v_add_u32_e32 v20, v20, v146
	v_add_u32_e32 v21, v21, v146
	v_cndmask_b32_e32 v20, v142, v20, vcc
	v_cndmask_b32_e32 v21, v144, v21, vcc
	global_load_lds_dwordx4 v20, s[42:43]
	s_mov_b32 m0, s52
	s_nop 0
	global_load_lds_dwordx4 v21, s[42:43]
	s_waitcnt vmcnt(8)
	s_waitcnt lgkmcnt(0)
	s_barrier
	s_setprio 1
	v_mfma_scale_f32_16x16x128_f8f6f4 v[56:59], v[152:159], v[64:71], 0, v149, v149 op_sel_hi:[0,0,0]
	v_mfma_scale_f32_16x16x128_f8f6f4 v[234:237], v[166:173], v[80:87], 0, v149, v149 op_sel_hi:[0,0,0]
	v_mfma_scale_f32_16x16x128_f8f6f4 v[8:11], v[152:159], v[88:95], 0, v149, v149 op_sel_hi:[0,0,0]
	v_mfma_scale_f32_16x16x128_f8f6f4 v[206:209], v[166:173], v[64:71], 0, v149, v149 op_sel_hi:[0,0,0]
	v_mfma_scale_f32_16x16x128_f8f6f4 v[210:213], v[152:159], v[72:79], 0, v149, v149 op_sel_hi:[0,0,0]
	v_mfma_scale_f32_16x16x128_f8f6f4 v[214:217], v[166:173], v[72:79], 0, v149, v149 op_sel_hi:[0,0,0]
	v_mfma_scale_f32_16x16x128_f8f6f4 v[218:221], v[152:159], v[80:87], 0, v149, v149 op_sel_hi:[0,0,0]
	v_mfma_scale_f32_16x16x128_f8f6f4 v[238:241], v[166:173], v[88:95], 0, v149, v149 op_sel_hi:[0,0,0]
	s_setprio 0
	s_setprio 1
	v_mfma_scale_f32_16x16x128_f8f6f4 v[60:63], v[174:181], v[64:71], 0, v149, v149 op_sel_hi:[0,0,0]
	v_mfma_scale_f32_16x16x128_f8f6f4 v[52:55], v[182:189], v[64:71], 0, v149, v149 op_sel_hi:[0,0,0]
	v_mfma_scale_f32_16x16x128_f8f6f4 v[242:245], v[174:181], v[72:79], 0, v149, v149 op_sel_hi:[0,0,0]
	v_mfma_scale_f32_16x16x128_f8f6f4 v[246:249], v[182:189], v[72:79], 0, v149, v149 op_sel_hi:[0,0,0]
	v_mfma_scale_f32_16x16x128_f8f6f4 v[250:253], v[174:181], v[80:87], 0, v149, v149 op_sel_hi:[0,0,0]
	v_mfma_scale_f32_16x16x128_f8f6f4 v[136:139], v[182:189], v[80:87], 0, v149, v149 op_sel_hi:[0,0,0]
	v_mfma_scale_f32_16x16x128_f8f6f4 v[68:71], v[174:181], v[88:95], 0, v149, v149 op_sel_hi:[0,0,0]
	v_mfma_scale_f32_16x16x128_f8f6f4 v[64:67], v[182:189], v[88:95], 0, v149, v149 op_sel_hi:[0,0,0]
	s_setprio 0
	s_barrier
	s_add_i32 s44, 0, 0x18000
	s_add_i32 s45, 0, 0x1c000
	s_nop 0
	v_add_u32_e32 v16, s44, v133
	v_add_u32_e32 v20, s45, v133
	ds_read_b128 v[0:3], v16
	ds_read_b128 v[4:7], v16 offset:1024
	ds_read_b128 v[12:15], v16 offset:2048
	ds_read_b128 v[16:19], v16 offset:3072
	ds_read_b128 v[152:155], v20
	ds_read_b128 v[156:159], v20 offset:1024
	ds_read_b128 v[166:169], v20 offset:2048
	ds_read_b128 v[170:173], v20 offset:3072
	ds_read_b128 v[24:27], v131 offset:33792
	ds_read_b128 v[28:31], v131 offset:34816
	ds_read_b128 v[32:35], v131 offset:35840
	ds_read_b128 v[36:39], v131 offset:36864
	ds_read_b128 v[20:23], v131 offset:32768
	ds_read_b32 v72, v143 offset:512
	ds_read_b32 v73, v145 offset:512
	ds_read_b128 v[40:43], v131 offset:37888
	ds_read_b128 v[44:47], v131 offset:38912
	ds_read_b128 v[48:51], v131 offset:39936
	s_waitcnt lgkmcnt(0)
	v_add_u32_e32 v72, v72, v146
	s_mov_b32 m0, s53
	v_add_u32_e32 v73, v73, v146
	v_cndmask_b32_e32 v72, v141, v72, vcc
	v_cndmask_b32_e32 v73, v151, v73, vcc
	global_load_lds_dwordx4 v72, s[42:43]
	s_mov_b32 m0, s54
	s_nop 0
	global_load_lds_dwordx4 v73, s[42:43]
	s_waitcnt vmcnt(8)
	s_waitcnt lgkmcnt(0)
	s_barrier
	s_setprio 1
	v_mfma_scale_f32_16x16x128_f8f6f4 v[120:123], v[0:7], v[20:27], v[120:123], v149, v149 op_sel_hi:[0,0,0]
	v_mfma_scale_f32_16x16x128_f8f6f4 v[112:115], v[12:19], v[20:27], v[112:115], v149, v149 op_sel_hi:[0,0,0]
	v_mfma_scale_f32_16x16x128_f8f6f4 v[104:107], v[0:7], v[28:35], v[104:107], v149, v149 op_sel_hi:[0,0,0]
	v_mfma_scale_f32_16x16x128_f8f6f4 v[96:99], v[12:19], v[28:35], v[96:99], v149, v149 op_sel_hi:[0,0,0]
	v_mfma_scale_f32_16x16x128_f8f6f4 v[88:91], v[0:7], v[36:43], v[160:163], v149, v149 op_sel_hi:[0,0,0]
	v_mfma_scale_f32_16x16x128_f8f6f4 v[80:83], v[12:19], v[36:43], v[222:225], v149, v149 op_sel_hi:[0,0,0]
	v_mfma_scale_f32_16x16x128_f8f6f4 v[72:75], v[0:7], v[44:51], v[226:229], v149, v149 op_sel_hi:[0,0,0]
	v_mfma_scale_f32_16x16x128_f8f6f4 v[230:233], v[12:19], v[44:51], v[230:233], v149, v149 op_sel_hi:[0,0,0]
	s_setprio 0
	s_setprio 1
	v_mfma_scale_f32_16x16x128_f8f6f4 v[124:127], v[152:159], v[20:27], v[124:127], v149, v149 op_sel_hi:[0,0,0]
	v_mfma_scale_f32_16x16x128_f8f6f4 v[116:119], v[166:173], v[20:27], v[116:119], v149, v149 op_sel_hi:[0,0,0]
	v_mfma_scale_f32_16x16x128_f8f6f4 v[108:111], v[152:159], v[28:35], v[108:111], v149, v149 op_sel_hi:[0,0,0]
	v_mfma_scale_f32_16x16x128_f8f6f4 v[100:103], v[166:173], v[28:35], v[100:103], v149, v149 op_sel_hi:[0,0,0]
	v_mfma_scale_f32_16x16x128_f8f6f4 v[92:95], v[152:159], v[36:43], v[190:193], v149, v149 op_sel_hi:[0,0,0]
	v_mfma_scale_f32_16x16x128_f8f6f4 v[84:87], v[166:173], v[36:43], v[194:197], v149, v149 op_sel_hi:[0,0,0]
	v_mfma_scale_f32_16x16x128_f8f6f4 v[76:79], v[152:159], v[44:51], v[198:201], v149, v149 op_sel_hi:[0,0,0]
	v_mfma_scale_f32_16x16x128_f8f6f4 v[20:23], v[166:173], v[44:51], v[202:205], v149, v149 op_sel_hi:[0,0,0]
	s_setprio 0
	s_barrier
	s_add_i32 s42, s44, s46
	s_mov_b32 m0, s42
	ds_read_b128 v[174:177], v131 offset:49152
	ds_read_b128 v[178:181], v131 offset:50176
	ds_read_b128 v[182:185], v131 offset:51200
	ds_read_b128 v[186:189], v131 offset:52224
	ds_read_b128 v[190:193], v131 offset:53248
	ds_read_b128 v[194:197], v131 offset:54272
	ds_read_b128 v[198:201], v131 offset:55296
	ds_read_b128 v[202:205], v131 offset:56320
	global_load_lds_dwordx4 v130, s[38:39]
	s_add_i32 m0, s42, 0x2000
	s_nop 0
	global_load_lds_dwordx4 v132, s[38:39]
	s_add_u32 s38, s38, 0x20000
	s_addc_u32 s39, s39, 0
	s_add_i32 s42, s45, s46
	s_mov_b32 m0, s42
	s_nop 0
	global_load_lds_dwordx4 v130, s[38:39]
	s_add_i32 m0, s42, 0x2000
	s_nop 0
	global_load_lds_dwordx4 v132, s[38:39]
	ds_read_b32 v24, v143
	ds_read_b32 v25, v145
	s_mov_b32 m0, s59
	s_waitcnt lgkmcnt(0)
	v_add_u32_e32 v24, v24, v146
	v_add_u32_e32 v25, v25, v146
	v_cndmask_b32_e32 v24, v142, v24, vcc
	v_cndmask_b32_e32 v25, v144, v25, vcc
	global_load_lds_dwordx4 v24, s[40:41]
	s_mov_b32 m0, s63
	s_nop 0
	global_load_lds_dwordx4 v25, s[40:41]
	s_waitcnt vmcnt(8)
	s_waitcnt lgkmcnt(0)
	s_barrier
	s_setprio 1
	v_mfma_scale_f32_16x16x128_f8f6f4 v[56:59], v[0:7], v[174:181], v[56:59], v149, v149 op_sel_hi:[0,0,0]
	v_mfma_scale_f32_16x16x128_f8f6f4 v[48:51], v[12:19], v[174:181], v[206:209], v149, v149 op_sel_hi:[0,0,0]
	v_mfma_scale_f32_16x16x128_f8f6f4 v[40:43], v[0:7], v[182:189], v[210:213], v149, v149 op_sel_hi:[0,0,0]
	v_mfma_scale_f32_16x16x128_f8f6f4 v[32:35], v[12:19], v[182:189], v[214:217], v149, v149 op_sel_hi:[0,0,0]
	v_mfma_scale_f32_16x16x128_f8f6f4 v[24:27], v[0:7], v[190:197], v[218:221], v149, v149 op_sel_hi:[0,0,0]
	v_mfma_scale_f32_16x16x128_f8f6f4 v[234:237], v[12:19], v[190:197], v[234:237], v149, v149 op_sel_hi:[0,0,0]
	v_mfma_scale_f32_16x16x128_f8f6f4 v[8:11], v[0:7], v[198:205], v[8:11], v149, v149 op_sel_hi:[0,0,0]
	v_mfma_scale_f32_16x16x128_f8f6f4 v[0:3], v[12:19], v[198:205], v[238:241], v149, v149 op_sel_hi:[0,0,0]
	s_setprio 0
	s_setprio 1
	v_mfma_scale_f32_16x16x128_f8f6f4 v[60:63], v[152:159], v[174:181], v[60:63], v149, v149 op_sel_hi:[0,0,0]
	v_mfma_scale_f32_16x16x128_f8f6f4 v[52:55], v[166:173], v[174:181], v[52:55], v149, v149 op_sel_hi:[0,0,0]
	v_mfma_scale_f32_16x16x128_f8f6f4 v[44:47], v[152:159], v[182:189], v[242:245], v149, v149 op_sel_hi:[0,0,0]
	v_mfma_scale_f32_16x16x128_f8f6f4 v[36:39], v[166:173], v[182:189], v[246:249], v149, v149 op_sel_hi:[0,0,0]
	v_mfma_scale_f32_16x16x128_f8f6f4 v[28:31], v[152:159], v[190:197], v[250:253], v149, v149 op_sel_hi:[0,0,0]
	v_mfma_scale_f32_16x16x128_f8f6f4 v[16:19], v[166:173], v[190:197], v[136:139], v149, v149 op_sel_hi:[0,0,0]
	v_mfma_scale_f32_16x16x128_f8f6f4 v[12:15], v[152:159], v[198:205], v[68:71], v149, v149 op_sel_hi:[0,0,0]
	v_mfma_scale_f32_16x16x128_f8f6f4 v[4:7], v[166:173], v[198:205], v[64:67], v149, v149 op_sel_hi:[0,0,0]
	s_setprio 0
	s_barrier
	s_add_i32 s29, s29, 2
	s_add_u32 s21, s21, 0x100
	s_addc_u32 s27, s27, 0
	s_add_u32 s30, s30, 0x100
	s_addc_u32 s31, s31, 0
	s_cmp_gt_u32 s29, 5

.LBB0_1875:
	s_ashr_i32 s27, s26, 31
	s_lshl_b64 s[26:27], s[26:27], 19
	s_add_u32 s21, s56, s26
	s_addc_u32 s30, s57, s27
	s_ashr_i32 s29, s28, 31
	s_lshl_b64 s[26:27], s[28:29], 7
	s_add_u32 s21, s21, s26
	s_addc_u32 s27, s30, s27
	s_add_u32 s26, s21, s58
	s_addc_u32 s27, s27, 0
	s_mov_b32 s98, 0x44800000
	s_mov_b32 s99, 0x44800000
	v_pk_mul_f32 v[64:65], v[120:121], s[10:11] op_sel_hi:[1,0]
	v_pk_mul_f32 v[66:67], v[122:123], s[10:11] op_sel_hi:[1,0]
	v_pk_mul_f32 v[68:69], v[112:113], s[10:11] op_sel_hi:[1,0]
	v_pk_mul_f32 v[70:71], v[114:115], s[10:11] op_sel_hi:[1,0]
	v_exp_f32_e32 v64, v64
	v_exp_f32_e32 v65, v65
	v_exp_f32_e32 v66, v66
	v_exp_f32_e32 v67, v67
	v_exp_f32_e32 v68, v68
	v_exp_f32_e32 v69, v69
	v_exp_f32_e32 v70, v70
	v_exp_f32_e32 v71, v71
	v_pk_fma_f32 v[64:65], v[64:65], s[98:99], s[98:99]
	v_pk_fma_f32 v[66:67], v[66:67], s[98:99], s[98:99]
	v_pk_fma_f32 v[68:69], v[68:69], s[98:99], s[98:99]
	v_pk_fma_f32 v[70:71], v[70:71], s[98:99], s[98:99]
	v_rcp_f32_e32 v64, v64
	v_rcp_f32_e32 v65, v65
	v_pk_mul_f32 v[120:121], v[120:121], v[124:125]
	v_rcp_f32_e32 v66, v66
	v_rcp_f32_e32 v67, v67
	v_pk_mul_f32 v[122:123], v[122:123], v[126:127]
	v_rcp_f32_e32 v68, v68
	v_rcp_f32_e32 v69, v69
	v_pk_mul_f32 v[112:113], v[112:113], v[116:117]
	v_rcp_f32_e32 v70, v70
	v_rcp_f32_e32 v71, v71
	v_pk_mul_f32 v[114:115], v[114:115], v[118:119]
	v_add_u32_e32 v124, v128, v134
	v_pk_mul_f32 v[120:121], v[120:121], v[64:65]
	v_pk_mul_f32 v[122:123], v[122:123], v[66:67]
	v_pk_mul_f32 v[112:113], v[112:113], v[68:69]
	v_pk_mul_f32 v[114:115], v[114:115], v[70:71]
	v_med3_f32 v120, v120, s67, v150
	v_med3_f32 v121, v121, s67, v150
	v_med3_f32 v122, v122, s67, v150
	v_med3_f32 v123, v123, s67, v150
	v_med3_f32 v112, v112, s67, v150
	v_med3_f32 v113, v113, s67, v150
	v_med3_f32 v114, v114, s67, v150
	v_med3_f32 v115, v115, s67, v150
	v_cvt_pk_fp8_f32 v136, v120, v121
	v_cvt_pk_fp8_f32 v137, v112, v113
	v_cvt_pk_fp8_f32 v136, v122, v123 op_sel:[0,0,1]
	v_cvt_pk_fp8_f32 v137, v114, v115 op_sel:[0,0,1]
	s_mov_b32 s100, s26
	s_mov_b32 s101, s27
	global_store_dwordx2 v124, v[136:137], s[100:101] nt
	v_pk_mul_f32 v[64:65], v[104:105], s[10:11] op_sel_hi:[1,0]
	v_pk_mul_f32 v[66:67], v[106:107], s[10:11] op_sel_hi:[1,0]
	v_pk_mul_f32 v[68:69], v[96:97], s[10:11] op_sel_hi:[1,0]
	v_pk_mul_f32 v[70:71], v[98:99], s[10:11] op_sel_hi:[1,0]
	v_exp_f32_e32 v64, v64
	v_exp_f32_e32 v65, v65
	v_exp_f32_e32 v66, v66
	v_exp_f32_e32 v67, v67
	v_exp_f32_e32 v68, v68
	v_exp_f32_e32 v69, v69
	v_exp_f32_e32 v70, v70
	v_exp_f32_e32 v71, v71
	v_pk_fma_f32 v[64:65], v[64:65], s[98:99], s[98:99]
	v_pk_fma_f32 v[66:67], v[66:67], s[98:99], s[98:99]
	v_pk_fma_f32 v[68:69], v[68:69], s[98:99], s[98:99]
	v_pk_fma_f32 v[70:71], v[70:71], s[98:99], s[98:99]
	v_rcp_f32_e32 v64, v64
	v_rcp_f32_e32 v65, v65
	v_pk_mul_f32 v[104:105], v[104:105], v[108:109]
	v_rcp_f32_e32 v66, v66
	v_rcp_f32_e32 v67, v67
	v_pk_mul_f32 v[106:107], v[106:107], v[110:111]
	v_rcp_f32_e32 v68, v68
	v_rcp_f32_e32 v69, v69
	v_pk_mul_f32 v[96:97], v[96:97], v[100:101]
	v_rcp_f32_e32 v70, v70
	v_rcp_f32_e32 v71, v71
	v_pk_mul_f32 v[98:99], v[98:99], v[102:103]
	v_pk_mul_f32 v[104:105], v[104:105], v[64:65]
	v_pk_mul_f32 v[106:107], v[106:107], v[66:67]
	v_pk_mul_f32 v[96:97], v[96:97], v[68:69]
	v_pk_mul_f32 v[98:99], v[98:99], v[70:71]
	v_med3_f32 v104, v104, s67, v150
	v_med3_f32 v105, v105, s67, v150
	v_med3_f32 v106, v106, s67, v150
	v_med3_f32 v107, v107, s67, v150
	v_med3_f32 v96, v96, s67, v150
	v_med3_f32 v97, v97, s67, v150
	v_med3_f32 v98, v98, s67, v150
	v_med3_f32 v99, v99, s67, v150
	v_cvt_pk_fp8_f32 v140, v104, v105
	v_cvt_pk_fp8_f32 v141, v96, v97
	v_cvt_pk_fp8_f32 v140, v106, v107 op_sel:[0,0,1]
	v_cvt_pk_fp8_f32 v141, v98, v99 op_sel:[0,0,1]
	s_add_u32 s100, s26, 0x8000
	s_addc_u32 s101, s27, 0
	global_store_dwordx2 v124, v[140:141], s[100:101] nt
	v_pk_mul_f32 v[64:65], v[88:89], s[10:11] op_sel_hi:[1,0]
	v_pk_mul_f32 v[66:67], v[90:91], s[10:11] op_sel_hi:[1,0]
	v_pk_mul_f32 v[68:69], v[80:81], s[10:11] op_sel_hi:[1,0]
	v_pk_mul_f32 v[70:71], v[82:83], s[10:11] op_sel_hi:[1,0]
	v_exp_f32_e32 v64, v64
	v_exp_f32_e32 v65, v65
	v_exp_f32_e32 v66, v66
	v_exp_f32_e32 v67, v67
	v_exp_f32_e32 v68, v68
	v_exp_f32_e32 v69, v69
	v_exp_f32_e32 v70, v70
	v_exp_f32_e32 v71, v71
	v_pk_fma_f32 v[64:65], v[64:65], s[98:99], s[98:99]
	v_pk_fma_f32 v[66:67], v[66:67], s[98:99], s[98:99]
	v_pk_fma_f32 v[68:69], v[68:69], s[98:99], s[98:99]
	v_pk_fma_f32 v[70:71], v[70:71], s[98:99], s[98:99]
	v_rcp_f32_e32 v64, v64
	v_rcp_f32_e32 v65, v65
	v_pk_mul_f32 v[88:89], v[88:89], v[92:93]
	v_rcp_f32_e32 v66, v66
	v_rcp_f32_e32 v67, v67
	v_pk_mul_f32 v[90:91], v[90:91], v[94:95]
	v_rcp_f32_e32 v68, v68
	v_rcp_f32_e32 v69, v69
	v_pk_mul_f32 v[80:81], v[80:81], v[84:85]
	v_rcp_f32_e32 v70, v70
	v_rcp_f32_e32 v71, v71
	v_pk_mul_f32 v[82:83], v[82:83], v[86:87]
	v_pk_mul_f32 v[88:89], v[88:89], v[64:65]
	v_pk_mul_f32 v[90:91], v[90:91], v[66:67]
	v_pk_mul_f32 v[80:81], v[80:81], v[68:69]
	v_pk_mul_f32 v[82:83], v[82:83], v[70:71]
	v_med3_f32 v88, v88, s67, v150
	v_med3_f32 v89, v89, s67, v150
	v_med3_f32 v90, v90, s67, v150
	v_med3_f32 v91, v91, s67, v150
	v_med3_f32 v80, v80, s67, v150
	v_med3_f32 v81, v81, s67, v150
	v_med3_f32 v82, v82, s67, v150
	v_med3_f32 v83, v83, s67, v150
	v_cvt_pk_fp8_f32 v136, v88, v89
	v_cvt_pk_fp8_f32 v137, v80, v81
	v_cvt_pk_fp8_f32 v136, v90, v91 op_sel:[0,0,1]
	v_cvt_pk_fp8_f32 v137, v82, v83 op_sel:[0,0,1]
	s_add_u32 s100, s26, 0x10000
	s_addc_u32 s101, s27, 0
	global_store_dwordx2 v124, v[136:137], s[100:101] nt
	v_pk_mul_f32 v[64:65], v[72:73], s[10:11] op_sel_hi:[1,0]
	v_pk_mul_f32 v[66:67], v[74:75], s[10:11] op_sel_hi:[1,0]
	v_pk_mul_f32 v[68:69], v[230:231], s[10:11] op_sel_hi:[1,0]
	v_pk_mul_f32 v[70:71], v[232:233], s[10:11] op_sel_hi:[1,0]
	v_exp_f32_e32 v64, v64
	v_exp_f32_e32 v65, v65
	v_exp_f32_e32 v66, v66
	v_exp_f32_e32 v67, v67
	v_exp_f32_e32 v68, v68
	v_exp_f32_e32 v69, v69
	v_exp_f32_e32 v70, v70
	v_exp_f32_e32 v71, v71
	v_pk_fma_f32 v[64:65], v[64:65], s[98:99], s[98:99]
	v_pk_fma_f32 v[66:67], v[66:67], s[98:99], s[98:99]
	v_pk_fma_f32 v[68:69], v[68:69], s[98:99], s[98:99]
	v_pk_fma_f32 v[70:71], v[70:71], s[98:99], s[98:99]
	v_rcp_f32_e32 v64, v64
	v_rcp_f32_e32 v65, v65
	v_pk_mul_f32 v[72:73], v[72:73], v[76:77]
	v_rcp_f32_e32 v66, v66
	v_rcp_f32_e32 v67, v67
	v_pk_mul_f32 v[74:75], v[74:75], v[78:79]
	v_rcp_f32_e32 v68, v68
	v_rcp_f32_e32 v69, v69
	v_pk_mul_f32 v[230:231], v[230:231], v[20:21]
	v_rcp_f32_e32 v70, v70
	v_rcp_f32_e32 v71, v71
	v_pk_mul_f32 v[232:233], v[232:233], v[22:23]
	v_pk_mul_f32 v[72:73], v[72:73], v[64:65]
	v_pk_mul_f32 v[74:75], v[74:75], v[66:67]
	v_pk_mul_f32 v[230:231], v[230:231], v[68:69]
	v_pk_mul_f32 v[232:233], v[232:233], v[70:71]
	v_med3_f32 v72, v72, s67, v150
	v_med3_f32 v73, v73, s67, v150
	v_med3_f32 v74, v74, s67, v150
	v_med3_f32 v75, v75, s67, v150
	v_med3_f32 v230, v230, s67, v150
	v_med3_f32 v231, v231, s67, v150
	v_med3_f32 v232, v232, s67, v150
	v_med3_f32 v233, v233, s67, v150
	v_cvt_pk_fp8_f32 v140, v72, v73
	v_cvt_pk_fp8_f32 v141, v230, v231
	v_cvt_pk_fp8_f32 v140, v74, v75 op_sel:[0,0,1]
	v_cvt_pk_fp8_f32 v141, v232, v233 op_sel:[0,0,1]
	s_add_u32 s100, s26, 0x18000
	s_addc_u32 s101, s27, 0
	global_store_dwordx2 v124, v[140:141], s[100:101] nt
	v_pk_mul_f32 v[64:65], v[56:57], s[10:11] op_sel_hi:[1,0]
	v_pk_mul_f32 v[66:67], v[58:59], s[10:11] op_sel_hi:[1,0]
	v_pk_mul_f32 v[68:69], v[48:49], s[10:11] op_sel_hi:[1,0]
	v_pk_mul_f32 v[70:71], v[50:51], s[10:11] op_sel_hi:[1,0]
	v_exp_f32_e32 v64, v64
	v_exp_f32_e32 v65, v65
	v_exp_f32_e32 v66, v66
	v_exp_f32_e32 v67, v67
	v_exp_f32_e32 v68, v68
	v_exp_f32_e32 v69, v69
	v_exp_f32_e32 v70, v70
	v_exp_f32_e32 v71, v71
	v_pk_fma_f32 v[64:65], v[64:65], s[98:99], s[98:99]
	v_pk_fma_f32 v[66:67], v[66:67], s[98:99], s[98:99]
	v_pk_fma_f32 v[68:69], v[68:69], s[98:99], s[98:99]
	v_pk_fma_f32 v[70:71], v[70:71], s[98:99], s[98:99]
	v_rcp_f32_e32 v64, v64
	v_rcp_f32_e32 v65, v65
	v_pk_mul_f32 v[56:57], v[56:57], v[60:61]
	v_rcp_f32_e32 v66, v66
	v_rcp_f32_e32 v67, v67
	v_pk_mul_f32 v[58:59], v[58:59], v[62:63]
	v_rcp_f32_e32 v68, v68
	v_rcp_f32_e32 v69, v69
	v_pk_mul_f32 v[48:49], v[48:49], v[52:53]
	v_rcp_f32_e32 v70, v70
	v_rcp_f32_e32 v71, v71
	v_pk_mul_f32 v[50:51], v[50:51], v[54:55]
	v_pk_mul_f32 v[56:57], v[56:57], v[64:65]
	v_pk_mul_f32 v[58:59], v[58:59], v[66:67]
	v_pk_mul_f32 v[48:49], v[48:49], v[68:69]
	v_pk_mul_f32 v[50:51], v[50:51], v[70:71]
	v_med3_f32 v56, v56, s67, v150
	v_med3_f32 v57, v57, s67, v150
	v_med3_f32 v58, v58, s67, v150
	v_med3_f32 v59, v59, s67, v150
	v_med3_f32 v48, v48, s67, v150
	v_med3_f32 v49, v49, s67, v150
	v_med3_f32 v50, v50, s67, v150
	v_med3_f32 v51, v51, s67, v150
	v_cvt_pk_fp8_f32 v136, v56, v57
	v_cvt_pk_fp8_f32 v137, v48, v49
	v_cvt_pk_fp8_f32 v136, v58, v59 op_sel:[0,0,1]
	v_cvt_pk_fp8_f32 v137, v50, v51 op_sel:[0,0,1]
	s_add_u32 s100, s26, 0x40000
	s_addc_u32 s101, s27, 0
	global_store_dwordx2 v124, v[136:137], s[100:101] nt
	v_pk_mul_f32 v[64:65], v[40:41], s[10:11] op_sel_hi:[1,0]
	v_pk_mul_f32 v[66:67], v[42:43], s[10:11] op_sel_hi:[1,0]
	v_pk_mul_f32 v[68:69], v[32:33], s[10:11] op_sel_hi:[1,0]
	v_pk_mul_f32 v[70:71], v[34:35], s[10:11] op_sel_hi:[1,0]
	v_exp_f32_e32 v64, v64
	v_exp_f32_e32 v65, v65
	v_exp_f32_e32 v66, v66
	v_exp_f32_e32 v67, v67
	v_exp_f32_e32 v68, v68
	v_exp_f32_e32 v69, v69
	v_exp_f32_e32 v70, v70
	v_exp_f32_e32 v71, v71
	v_pk_fma_f32 v[64:65], v[64:65], s[98:99], s[98:99]
	v_pk_fma_f32 v[66:67], v[66:67], s[98:99], s[98:99]
	v_pk_fma_f32 v[68:69], v[68:69], s[98:99], s[98:99]
	v_pk_fma_f32 v[70:71], v[70:71], s[98:99], s[98:99]
	v_rcp_f32_e32 v64, v64
	v_rcp_f32_e32 v65, v65
	v_pk_mul_f32 v[40:41], v[40:41], v[44:45]
	v_rcp_f32_e32 v66, v66
	v_rcp_f32_e32 v67, v67
	v_pk_mul_f32 v[42:43], v[42:43], v[46:47]
	v_rcp_f32_e32 v68, v68
	v_rcp_f32_e32 v69, v69
	v_pk_mul_f32 v[32:33], v[32:33], v[36:37]
	v_rcp_f32_e32 v70, v70
	v_rcp_f32_e32 v71, v71
	v_pk_mul_f32 v[34:35], v[34:35], v[38:39]
	v_pk_mul_f32 v[40:41], v[40:41], v[64:65]
	v_pk_mul_f32 v[42:43], v[42:43], v[66:67]
	v_pk_mul_f32 v[32:33], v[32:33], v[68:69]
	v_pk_mul_f32 v[34:35], v[34:35], v[70:71]
	v_med3_f32 v40, v40, s67, v150
	v_med3_f32 v41, v41, s67, v150
	v_med3_f32 v42, v42, s67, v150
	v_med3_f32 v43, v43, s67, v150
	v_med3_f32 v32, v32, s67, v150
	v_med3_f32 v33, v33, s67, v150
	v_med3_f32 v34, v34, s67, v150
	v_med3_f32 v35, v35, s67, v150
	v_cvt_pk_fp8_f32 v140, v40, v41
	v_cvt_pk_fp8_f32 v141, v32, v33
	v_cvt_pk_fp8_f32 v140, v42, v43 op_sel:[0,0,1]
	v_cvt_pk_fp8_f32 v141, v34, v35 op_sel:[0,0,1]
	s_add_u32 s100, s26, 0x48000
	s_addc_u32 s101, s27, 0
	global_store_dwordx2 v124, v[140:141], s[100:101] nt
	v_pk_mul_f32 v[64:65], v[24:25], s[10:11] op_sel_hi:[1,0]
	v_pk_mul_f32 v[66:67], v[26:27], s[10:11] op_sel_hi:[1,0]
	v_pk_mul_f32 v[68:69], v[234:235], s[10:11] op_sel_hi:[1,0]
	v_pk_mul_f32 v[70:71], v[236:237], s[10:11] op_sel_hi:[1,0]
	v_exp_f32_e32 v64, v64
	v_exp_f32_e32 v65, v65
	v_exp_f32_e32 v66, v66
	v_exp_f32_e32 v67, v67
	v_exp_f32_e32 v68, v68
	v_exp_f32_e32 v69, v69
	v_exp_f32_e32 v70, v70
	v_exp_f32_e32 v71, v71
	v_pk_fma_f32 v[64:65], v[64:65], s[98:99], s[98:99]
	v_pk_fma_f32 v[66:67], v[66:67], s[98:99], s[98:99]
	v_pk_fma_f32 v[68:69], v[68:69], s[98:99], s[98:99]
	v_pk_fma_f32 v[70:71], v[70:71], s[98:99], s[98:99]
	v_rcp_f32_e32 v64, v64
	v_rcp_f32_e32 v65, v65
	v_pk_mul_f32 v[24:25], v[24:25], v[28:29]
	v_rcp_f32_e32 v66, v66
	v_rcp_f32_e32 v67, v67
	v_pk_mul_f32 v[26:27], v[26:27], v[30:31]
	v_rcp_f32_e32 v68, v68
	v_rcp_f32_e32 v69, v69
	v_pk_mul_f32 v[234:235], v[234:235], v[16:17]
	v_rcp_f32_e32 v70, v70
	v_rcp_f32_e32 v71, v71
	v_pk_mul_f32 v[236:237], v[236:237], v[18:19]
	v_pk_mul_f32 v[24:25], v[24:25], v[64:65]
	v_pk_mul_f32 v[26:27], v[26:27], v[66:67]
	v_pk_mul_f32 v[234:235], v[234:235], v[68:69]
	v_pk_mul_f32 v[236:237], v[236:237], v[70:71]
	v_med3_f32 v24, v24, s67, v150
	v_med3_f32 v25, v25, s67, v150
	v_med3_f32 v26, v26, s67, v150
	v_med3_f32 v27, v27, s67, v150
	v_med3_f32 v234, v234, s67, v150
	v_med3_f32 v235, v235, s67, v150
	v_med3_f32 v236, v236, s67, v150
	v_med3_f32 v237, v237, s67, v150
	v_cvt_pk_fp8_f32 v136, v24, v25
	v_cvt_pk_fp8_f32 v137, v234, v235
	v_cvt_pk_fp8_f32 v136, v26, v27 op_sel:[0,0,1]
	v_cvt_pk_fp8_f32 v137, v236, v237 op_sel:[0,0,1]
	s_add_u32 s100, s26, 0x50000
	s_addc_u32 s101, s27, 0
	global_store_dwordx2 v124, v[136:137], s[100:101] nt
	v_pk_mul_f32 v[64:65], v[8:9], s[10:11] op_sel_hi:[1,0]
	v_pk_mul_f32 v[66:67], v[10:11], s[10:11] op_sel_hi:[1,0]
	v_pk_mul_f32 v[68:69], v[0:1], s[10:11] op_sel_hi:[1,0]
	v_pk_mul_f32 v[70:71], v[2:3], s[10:11] op_sel_hi:[1,0]
	v_exp_f32_e32 v64, v64
	v_exp_f32_e32 v65, v65
	v_exp_f32_e32 v66, v66
	v_exp_f32_e32 v67, v67
	v_exp_f32_e32 v68, v68
	v_exp_f32_e32 v69, v69
	v_exp_f32_e32 v70, v70
	v_exp_f32_e32 v71, v71
	v_pk_fma_f32 v[64:65], v[64:65], s[98:99], s[98:99]
	v_pk_fma_f32 v[66:67], v[66:67], s[98:99], s[98:99]
	v_pk_fma_f32 v[68:69], v[68:69], s[98:99], s[98:99]
	v_pk_fma_f32 v[70:71], v[70:71], s[98:99], s[98:99]
	v_rcp_f32_e32 v64, v64
	v_rcp_f32_e32 v65, v65
	v_pk_mul_f32 v[8:9], v[8:9], v[12:13]
	v_rcp_f32_e32 v66, v66
	v_rcp_f32_e32 v67, v67
	v_pk_mul_f32 v[10:11], v[10:11], v[14:15]
	v_rcp_f32_e32 v68, v68
	v_rcp_f32_e32 v69, v69
	v_pk_mul_f32 v[0:1], v[0:1], v[4:5]
	v_rcp_f32_e32 v70, v70
	v_rcp_f32_e32 v71, v71
	v_pk_mul_f32 v[2:3], v[2:3], v[6:7]
	v_pk_mul_f32 v[8:9], v[8:9], v[64:65]
	v_pk_mul_f32 v[10:11], v[10:11], v[66:67]
	v_pk_mul_f32 v[0:1], v[0:1], v[68:69]
	v_pk_mul_f32 v[2:3], v[2:3], v[70:71]
	v_med3_f32 v8, v8, s67, v150
	v_med3_f32 v9, v9, s67, v150
	v_med3_f32 v10, v10, s67, v150
	v_med3_f32 v11, v11, s67, v150
	v_med3_f32 v0, v0, s67, v150
	v_med3_f32 v1, v1, s67, v150
	v_med3_f32 v2, v2, s67, v150
	v_med3_f32 v3, v3, s67, v150
	v_cvt_pk_fp8_f32 v140, v8, v9
	v_cvt_pk_fp8_f32 v141, v0, v1
	v_cvt_pk_fp8_f32 v140, v10, v11 op_sel:[0,0,1]
	v_cvt_pk_fp8_f32 v141, v2, v3 op_sel:[0,0,1]
	s_add_u32 s100, s26, 0x58000
	s_addc_u32 s101, s27, 0
	global_store_dwordx2 v124, v[140:141], s[100:101] nt
	s_andn2_b64 vcc, exec, s[4:5]
	s_cbranch_vccnz .LBB0_1878
	ds_read2st64_b32 v[142:143], v143 offset1:2
	ds_read2st64_b32 v[144:145], v145 offset1:2
	s_andn2_b64 vcc, exec, s[14:15]
	s_cbranch_vccnz .LBB0_1867
	s_barrier
	s_branch .LBB0_1867
